# grid barrier: the last XCD leader bumps every XCC release word itself (one release hop less); on top of the 4+4 staging
# baseline (speedup 1.0000x reference)
.LBB0_172:
	s_or_b64 exec, exec, s[10:11]
	v_cvt_f32_u32_e32 v3, v0
	s_waitcnt vmcnt(0)
	v_readfirstlane_b32 s8, v2
	s_add_u32 s10, s18, 0xf81a900
	s_addc_u32 s11, s19, 0
	v_rcp_iflag_f32_e32 v3, v3
	v_add_u32_e32 v1, s8, v1
	v_add_u32_e32 v4, 1, v1
	s_mov_b64 s[12:13], -1
	v_mul_f32_e32 v2, 0x4f7ffffe, v3
	v_cvt_u32_f32_e32 v2, v2
	v_sub_u32_e32 v3, 0, v0
	v_mul_lo_u32 v3, v3, v2
	v_mul_hi_u32 v3, v2, v3
	v_add_u32_e32 v2, v2, v3
	v_mul_hi_u32 v2, v1, v2
	v_mul_lo_u32 v3, v2, v0
	v_sub_u32_e32 v1, v1, v3
	v_add_u32_e32 v5, 1, v2
	v_cmp_ge_u32_e32 vcc, v1, v0
	v_sub_u32_e32 v3, v1, v0
	s_nop 0
	v_cndmask_b32_e32 v2, v2, v5, vcc
	v_cndmask_b32_e32 v1, v1, v3, vcc
	v_add_u32_e32 v3, 1, v2
	v_cmp_ge_u32_e32 vcc, v1, v0
	s_nop 1
	v_cndmask_b32_e32 v2, v2, v3, vcc
	v_mul_lo_u32 v1, v0, v2
	v_add_u32_e32 v0, v1, v0
	v_cmp_ne_u32_e32 vcc, v4, v0
	v_mov_b64_e32 v[0:1], s[10:11]
	s_cbranch_vccnz .Lmy_xbf_notlast
	s_add_u32 s14, s10, 0xffffef00
	s_addc_u32 s15, s11, -1
	v_mov_b32_e32 v2, 1
	v_mov_b32_e32 v3, 0
	global_atomic_add v3, v2, s[14:15]
	global_atomic_add v3, v2, s[14:15] offset:256
	global_atomic_add v3, v2, s[14:15] offset:512
	global_atomic_add v3, v2, s[14:15] offset:768
	global_atomic_add v3, v2, s[14:15] offset:1024
	global_atomic_add v3, v2, s[14:15] offset:1280
	global_atomic_add v3, v2, s[14:15] offset:1536
	global_atomic_add v3, v2, s[14:15] offset:1792
	global_atomic_add v3, v2, s[14:15] offset:2048
	global_atomic_add v3, v2, s[14:15] offset:2304
	global_atomic_add v3, v2, s[14:15] offset:2560
	global_atomic_add v3, v2, s[14:15] offset:2816
	global_atomic_add v3, v2, s[14:15] offset:3072
	global_atomic_add v3, v2, s[14:15] offset:3328
	global_atomic_add v3, v2, s[14:15] offset:3584
	global_atomic_add v3, v2, s[14:15] offset:3840
.Lmy_xbf_notlast:
	s_and_saveexec_b64 s[8:9], vcc
	s_cbranch_execz .LBB0_184
	v_mov_b32_e32 v0, 0
	global_load_dword v1, v0, s[10:11] sc1
	s_mov_b64 s[16:17], 0
	s_waitcnt vmcnt(0)
	v_cmp_eq_u32_e32 vcc, v1, v2
	s_and_saveexec_b64 s[14:15], vcc
	s_cbranch_execz .LBB0_183
	s_add_u32 s12, s18, 0xf817600
	s_addc_u32 s13, s19, 0
	s_mov_b32 s30, 1
	s_branch .LBB0_176

.LBB0_186:
	s_or_b64 exec, exec, s[8:9]
	s_mov_b64 s[8:9], exec
	v_mbcnt_lo_u32_b32 v0, s8, 0
	v_mbcnt_hi_u32_b32 v0, s9, v0
	v_cmp_eq_u32_e32 vcc, 0, v0
	s_waitcnt vmcnt(0)
	buffer_inv sc1
	s_and_saveexec_b64 s[10:11], vcc
	s_cbranch_execz .LBB0_188
	s_bcnt1_i32_b64 s8, s[8:9]
	v_mov_b32_e32 v0, 0x2000
	v_mov_b32_e32 v1, s8
.LBB0_188:
	s_or_b64 exec, exec, s[10:11]
	s_waitcnt vmcnt(0)

.LBB0_341:
	s_or_b64 exec, exec, s[30:31]
	s_waitcnt vmcnt(0)
	v_readfirstlane_b32 s2, v2
	v_cvt_f32_u32_e32 v2, v0
	v_sub_u32_e32 v3, 0, v0
	v_add_u32_e32 v1, s2, v1
	v_readlane_b32 s4, v255, 20
	v_rcp_iflag_f32_e32 v2, v2
	v_readlane_b32 s5, v255, 21
	s_mov_b64 s[30:31], -1
	v_mul_f32_e32 v2, 0x4f7ffffe, v2
	v_cvt_u32_f32_e32 v2, v2
	v_mul_lo_u32 v3, v3, v2
	v_mul_hi_u32 v3, v2, v3
	v_add_u32_e32 v2, v2, v3
	v_mul_hi_u32 v2, v1, v2
	v_mul_lo_u32 v3, v2, v0
	v_sub_u32_e32 v3, v1, v3
	v_cmp_ge_u32_e32 vcc, v3, v0
	v_add_u32_e32 v4, 1, v2
	v_add_u32_e32 v1, 1, v1
	v_cndmask_b32_e32 v2, v2, v4, vcc
	v_sub_u32_e32 v4, v3, v0
	v_cndmask_b32_e32 v3, v3, v4, vcc
	v_cmp_ge_u32_e32 vcc, v3, v0
	v_add_u32_e32 v3, 1, v2
	s_nop 0
	v_cndmask_b32_e32 v2, v2, v3, vcc
	v_mul_lo_u32 v3, v0, v2
	v_add_u32_e32 v0, v3, v0
	v_cmp_ne_u32_e32 vcc, v1, v0
	v_mov_b64_e32 v[0:1], s[4:5]
	s_cbranch_vccnz .Lmy_xb0_notlast
	s_add_u32 s6, s4, 0xffffef00
	s_addc_u32 s7, s5, -1
	v_mov_b32_e32 v3, 1
	v_mov_b32_e32 v4, 0
	global_atomic_add v4, v3, s[6:7]
	global_atomic_add v4, v3, s[6:7] offset:256
	global_atomic_add v4, v3, s[6:7] offset:512
	global_atomic_add v4, v3, s[6:7] offset:768
	global_atomic_add v4, v3, s[6:7] offset:1024
	global_atomic_add v4, v3, s[6:7] offset:1280
	global_atomic_add v4, v3, s[6:7] offset:1536
	global_atomic_add v4, v3, s[6:7] offset:1792
	global_atomic_add v4, v3, s[6:7] offset:2048
	global_atomic_add v4, v3, s[6:7] offset:2304
	global_atomic_add v4, v3, s[6:7] offset:2560
	global_atomic_add v4, v3, s[6:7] offset:2816
	global_atomic_add v4, v3, s[6:7] offset:3072
	global_atomic_add v4, v3, s[6:7] offset:3328
	global_atomic_add v4, v3, s[6:7] offset:3584
	global_atomic_add v4, v3, s[6:7] offset:3840
.Lmy_xb0_notlast:
	s_and_saveexec_b64 s[22:23], vcc
	s_cbranch_execz .LBB0_353
	v_readlane_b32 s4, v255, 20
	v_readlane_b32 s5, v255, 21
	s_mov_b64 s[34:35], 0
	s_nop 3
	global_load_dword v0, v193, s[4:5] sc1
	s_waitcnt vmcnt(0)
	v_cmp_eq_u32_e32 vcc, v0, v2
	s_and_saveexec_b64 s[30:31], vcc
	s_cbranch_execz .LBB0_352
	s_mov_b32 s2, 1
	s_branch .LBB0_345

.LBB0_355:
	s_or_b64 exec, exec, s[22:23]
	s_mov_b64 s[22:23], exec
	v_mbcnt_lo_u32_b32 v0, s22, 0
	v_mbcnt_hi_u32_b32 v0, s23, v0
	v_cmp_eq_u32_e32 vcc, 0, v0
	s_waitcnt vmcnt(0)
	buffer_inv sc1
	s_and_saveexec_b64 s[30:31], vcc
	s_cbranch_execz .LBB0_357
	s_bcnt1_i32_b64 s2, s[22:23]
	v_readlane_b32 s4, v255, 16
	v_mov_b32_e32 v0, s2
	v_readlane_b32 s5, v255, 17
	s_nop 4
.LBB0_357:
	s_or_b64 exec, exec, s[30:31]
	s_waitcnt vmcnt(0)

.LBB0_806:
	s_or_b64 exec, exec, s[22:23]
	s_mov_b64 s[22:23], exec
	v_mbcnt_lo_u32_b32 v0, s22, 0
	v_mbcnt_hi_u32_b32 v0, s23, v0
	v_cmp_eq_u32_e32 vcc, 0, v0
	s_waitcnt vmcnt(0)
	buffer_inv sc1
	s_and_saveexec_b64 s[30:31], vcc
	s_cbranch_execz .LBB0_808
	s_bcnt1_i32_b64 s2, s[22:23]
	v_readlane_b32 s4, v255, 16
	v_mov_b32_e32 v0, s2
	v_readlane_b32 s5, v255, 17
	s_nop 4
.LBB0_808:
	s_or_b64 exec, exec, s[30:31]
	s_waitcnt vmcnt(0)

.LBB0_867:
	s_or_b64 exec, exec, s[22:23]
	s_mov_b64 s[22:23], exec
	v_mbcnt_lo_u32_b32 v0, s22, 0
	v_mbcnt_hi_u32_b32 v0, s23, v0
	v_cmp_eq_u32_e32 vcc, 0, v0
	s_waitcnt vmcnt(0)
	buffer_inv sc1
	s_and_saveexec_b64 s[30:31], vcc
	s_cbranch_execz .LBB0_869
	s_bcnt1_i32_b64 s2, s[22:23]
	v_readlane_b32 s4, v255, 16
	v_mov_b32_e32 v0, s2
	v_readlane_b32 s5, v255, 17
	s_nop 4
.LBB0_869:
	s_or_b64 exec, exec, s[30:31]
	s_waitcnt vmcnt(0)

.LBB0_1016:
	s_or_b64 exec, exec, s[22:23]
	s_mov_b64 s[22:23], exec
	v_mbcnt_lo_u32_b32 v0, s22, 0
	v_mbcnt_hi_u32_b32 v0, s23, v0
	v_cmp_eq_u32_e32 vcc, 0, v0
	s_waitcnt vmcnt(0)
	buffer_inv sc1
	s_and_saveexec_b64 s[30:31], vcc
	s_cbranch_execz .LBB0_1018
	s_bcnt1_i32_b64 s2, s[22:23]
	v_readlane_b32 s4, v255, 16
	v_mov_b32_e32 v0, s2
	v_readlane_b32 s5, v255, 17
	s_nop 4
.LBB0_1018:
	s_or_b64 exec, exec, s[30:31]
	s_waitcnt vmcnt(0)

.Lmy_xb4_notlast:
	s_and_saveexec_b64 s[22:23], vcc
	s_cbranch_execz .LBB0_1121
	v_readlane_b32 s4, v255, 20
	v_readlane_b32 s5, v255, 21
	s_mov_b64 s[36:37], 0
	s_nop 3
	global_load_dword v0, v193, s[4:5] sc1
	s_waitcnt vmcnt(0)
	v_cmp_eq_u32_e32 vcc, v0, v2
	s_and_saveexec_b64 s[30:31], vcc
	s_cbranch_execz .LBB0_1120
	s_mov_b32 s2, 1
	s_branch .LBB0_1113

.LBB0_1123:
	s_or_b64 exec, exec, s[22:23]
	s_mov_b64 s[22:23], exec
	v_mbcnt_lo_u32_b32 v0, s22, 0
	v_mbcnt_hi_u32_b32 v0, s23, v0
	v_cmp_eq_u32_e32 vcc, 0, v0
	s_waitcnt vmcnt(0)
	buffer_inv sc1
	s_and_saveexec_b64 s[30:31], vcc
	s_cbranch_execz .LBB0_1125
	s_bcnt1_i32_b64 s2, s[22:23]
	v_readlane_b32 s4, v255, 16
	v_mov_b32_e32 v0, s2
	v_readlane_b32 s5, v255, 17
	s_nop 4
.LBB0_1125:
	s_or_b64 exec, exec, s[30:31]
	s_waitcnt vmcnt(0)

.LBB0_1192:
	s_or_b64 exec, exec, s[34:35]
	s_waitcnt vmcnt(0)
	v_readfirstlane_b32 s2, v2
	v_cvt_f32_u32_e32 v2, v0
	v_sub_u32_e32 v3, 0, v0
	v_add_u32_e32 v1, s2, v1
	v_readlane_b32 s4, v255, 20
	v_rcp_iflag_f32_e32 v2, v2
	v_readlane_b32 s5, v255, 21
	s_mov_b64 s[34:35], -1
	v_mul_f32_e32 v2, 0x4f7ffffe, v2
	v_cvt_u32_f32_e32 v2, v2
	v_mul_lo_u32 v3, v3, v2
	v_mul_hi_u32 v3, v2, v3
	v_add_u32_e32 v2, v2, v3
	v_mul_hi_u32 v2, v1, v2
	v_mul_lo_u32 v3, v2, v0
	v_sub_u32_e32 v3, v1, v3
	v_cmp_ge_u32_e32 vcc, v3, v0
	v_add_u32_e32 v4, 1, v2
	v_add_u32_e32 v1, 1, v1
	v_cndmask_b32_e32 v2, v2, v4, vcc
	v_sub_u32_e32 v4, v3, v0
	v_cndmask_b32_e32 v3, v3, v4, vcc
	v_cmp_ge_u32_e32 vcc, v3, v0
	v_add_u32_e32 v3, 1, v2
	s_nop 0
	v_cndmask_b32_e32 v2, v2, v3, vcc
	v_mul_lo_u32 v3, v0, v2
	v_add_u32_e32 v0, v3, v0
	v_cmp_ne_u32_e32 vcc, v1, v0
	v_mov_b64_e32 v[0:1], s[4:5]
	s_cbranch_vccnz .Lmy_xb5_notlast
	s_add_u32 s6, s4, 0xffffef00
	s_addc_u32 s7, s5, -1
	v_mov_b32_e32 v3, 1
	v_mov_b32_e32 v4, 0
	global_atomic_add v4, v3, s[6:7]
	global_atomic_add v4, v3, s[6:7] offset:256
	global_atomic_add v4, v3, s[6:7] offset:512
	global_atomic_add v4, v3, s[6:7] offset:768
	global_atomic_add v4, v3, s[6:7] offset:1024
	global_atomic_add v4, v3, s[6:7] offset:1280
	global_atomic_add v4, v3, s[6:7] offset:1536
	global_atomic_add v4, v3, s[6:7] offset:1792
	global_atomic_add v4, v3, s[6:7] offset:2048
	global_atomic_add v4, v3, s[6:7] offset:2304
	global_atomic_add v4, v3, s[6:7] offset:2560
	global_atomic_add v4, v3, s[6:7] offset:2816
	global_atomic_add v4, v3, s[6:7] offset:3072
	global_atomic_add v4, v3, s[6:7] offset:3328
	global_atomic_add v4, v3, s[6:7] offset:3584
	global_atomic_add v4, v3, s[6:7] offset:3840
.Lmy_xb5_notlast:
	s_and_saveexec_b64 s[30:31], vcc
	s_cbranch_execz .LBB0_1204
	v_readlane_b32 s4, v255, 20
	v_readlane_b32 s5, v255, 21
	s_mov_b64 s[36:37], 0
	s_nop 3
	global_load_dword v0, v193, s[4:5] sc1
	s_waitcnt vmcnt(0)
	v_cmp_eq_u32_e32 vcc, v0, v2
	s_and_saveexec_b64 s[34:35], vcc
	s_cbranch_execz .LBB0_1203
	s_mov_b32 s2, 1
	s_branch .LBB0_1196

.LBB0_1206:
	s_or_b64 exec, exec, s[30:31]
	s_mov_b64 s[30:31], exec
	v_mbcnt_lo_u32_b32 v0, s30, 0
	v_mbcnt_hi_u32_b32 v0, s31, v0
	v_cmp_eq_u32_e32 vcc, 0, v0
	s_waitcnt vmcnt(0)
	buffer_inv sc1
	s_and_saveexec_b64 s[34:35], vcc
	s_cbranch_execz .LBB0_1208
	s_bcnt1_i32_b64 s2, s[30:31]
	v_readlane_b32 s4, v255, 16
	v_mov_b32_e32 v0, s2
	v_readlane_b32 s5, v255, 17
	s_nop 4
.LBB0_1208:
	s_or_b64 exec, exec, s[34:35]
	s_waitcnt vmcnt(0)

.LBB0_1383:
	s_bcnt1_i32_b64 s2, s[22:23]
	v_readlane_b32 s4, v255, 16
	v_mov_b32_e32 v0, s2
	v_readlane_b32 s5, v255, 17
	s_nop 4
	s_getpc_b64 s[98:99]
